# context-row norm after down projections: one batch of loads, DPP reduction (was 5 serialized round trips)
# speedup vs baseline: 1.0031x; 1.0031x over previous
.LBB0_731:
	s_add_i32 s25, s0, 0x4000
	s_lshl_b64 s[26:27], s[0:1], 12
	s_add_u32 s26, s39, s26
	s_addc_u32 s27, s28, s27
	s_cmpk_lt_i32 s25, 0x4000
	s_cselect_b32 s27, s24, s27
	s_cselect_b32 s26, s2, s26
	v_readfirstlane_b32 s42, v22
	v_readfirstlane_b32 s43, v23
	v_readfirstlane_b32 s98, v20
	v_readfirstlane_b32 s99, v21
	v_readfirstlane_b32 s24, v24
	v_readfirstlane_b32 s25, v25
	v_lshlrev_b32_e32 v82, 5, v244
	v_lshlrev_b32_e32 v83, 4, v244
	global_load_dwordx4 v[0:3], v82, s[26:27]
	global_load_dwordx4 v[4:7], v82, s[26:27] offset:16
	global_load_dwordx4 v[8:11], v82, s[26:27] offset:2048
	global_load_dwordx4 v[12:15], v82, s[26:27] offset:2064
	s_nop 4
	global_load_dwordx4 v[84:87], v82, s[42:43]
	global_load_dwordx4 v[88:91], v82, s[42:43] offset:16
	global_load_dwordx4 v[92:95], v82, s[42:43] offset:2048
	global_load_dwordx4 v[96:99], v82, s[42:43] offset:2064
	s_add_u32 s98, s98, 0x48000
	s_addc_u32 s99, s99, 0
	global_load_dwordx4 v[38:41], v82, s[98:99]
	global_load_dwordx4 v[42:45], v82, s[98:99] offset:16
	global_load_dwordx4 v[46:49], v82, s[98:99] offset:2048
	global_load_dwordx4 v[50:53], v82, s[98:99] offset:2064
	s_add_u32 s98, s98, 0x1000
	s_addc_u32 s99, s99, 0
	global_load_dwordx4 v[16:19], v82, s[98:99]
	global_load_dwordx4 v[20:23], v82, s[98:99] offset:16
	global_load_dwordx4 v[24:27], v82, s[98:99] offset:2048
	global_load_dwordx4 v[28:31], v82, s[98:99] offset:2064
	s_waitcnt vmcnt(0)
	v_pk_mul_f32 v[54:55], v[0:1], v[0:1]
	v_pk_mul_f32 v[56:57], v[2:3], v[2:3]
	v_pk_fma_f32 v[54:55], v[4:5], v[4:5], v[54:55]
	v_pk_fma_f32 v[56:57], v[6:7], v[6:7], v[56:57]
	v_pk_fma_f32 v[54:55], v[8:9], v[8:9], v[54:55]
	v_pk_fma_f32 v[56:57], v[10:11], v[10:11], v[56:57]
	v_pk_fma_f32 v[54:55], v[12:13], v[12:13], v[54:55]
	v_pk_fma_f32 v[56:57], v[14:15], v[14:15], v[56:57]
	v_pk_add_f32 v[54:55], v[54:55], v[56:57]
	v_pk_fma_f32 v[16:17], v[84:85], v[16:17], v[84:85]
	v_add_f32_e32 v54, v54, v55
	v_pk_fma_f32 v[18:19], v[86:87], v[18:19], v[86:87]
	v_pk_fma_f32 v[20:21], v[88:89], v[20:21], v[88:89]
	v_add_f32_dpp v54, v54, v54 quad_perm:[1,0,3,2] row_mask:0xf bank_mask:0xf
	v_pk_fma_f32 v[22:23], v[90:91], v[22:23], v[90:91]
	v_pk_fma_f32 v[24:25], v[92:93], v[24:25], v[92:93]
	v_add_f32_dpp v54, v54, v54 quad_perm:[2,3,0,1] row_mask:0xf bank_mask:0xf
	v_pk_fma_f32 v[26:27], v[94:95], v[26:27], v[94:95]
	v_pk_fma_f32 v[28:29], v[96:97], v[28:29], v[96:97]
	v_add_f32_dpp v54, v54, v54 row_half_mirror row_mask:0xf bank_mask:0xf
	v_pk_fma_f32 v[30:31], v[98:99], v[30:31], v[98:99]
	s_nop 1
	v_add_f32_dpp v54, v54, v54 row_mirror row_mask:0xf bank_mask:0xf
	s_nop 0
	v_mov_b32_e32 v55, v54
	s_nop 1
	v_permlane16_swap_b32_e32 v54, v55
	s_nop 0
	v_add_f32_e32 v54, v54, v55
	s_nop 0
	v_mov_b32_e32 v55, v54
	s_nop 1
	v_permlane32_swap_b32_e32 v54, v55
	s_nop 0
	v_add_f32_e32 v54, v54, v55
	v_fmamk_f32 v54, v54, 0x3a800000, v227
	v_rsq_f32_e32 v54, v54
	s_nop 1
	v_pk_mul_f32 v[0:1], v[0:1], v[54:55] op_sel_hi:[1,0]
	v_pk_mul_f32 v[2:3], v[2:3], v[54:55] op_sel_hi:[1,0]
	v_pk_mul_f32 v[4:5], v[4:5], v[54:55] op_sel_hi:[1,0]
	v_pk_mul_f32 v[6:7], v[6:7], v[54:55] op_sel_hi:[1,0]
	v_pk_mul_f32 v[8:9], v[8:9], v[54:55] op_sel_hi:[1,0]
	v_pk_mul_f32 v[10:11], v[10:11], v[54:55] op_sel_hi:[1,0]
	v_pk_mul_f32 v[12:13], v[12:13], v[54:55] op_sel_hi:[1,0]
	v_pk_mul_f32 v[14:15], v[14:15], v[54:55] op_sel_hi:[1,0]
	v_pk_fma_f32 v[0:1], v[0:1], v[16:17], v[38:39]
	v_pk_fma_f32 v[2:3], v[2:3], v[18:19], v[40:41]
	v_pk_fma_f32 v[4:5], v[4:5], v[20:21], v[42:43]
	v_pk_fma_f32 v[6:7], v[6:7], v[22:23], v[44:45]
	v_pk_fma_f32 v[8:9], v[8:9], v[24:25], v[46:47]
	v_pk_fma_f32 v[10:11], v[10:11], v[26:27], v[48:49]
	v_pk_fma_f32 v[12:13], v[12:13], v[28:29], v[50:51]
	v_pk_fma_f32 v[14:15], v[14:15], v[30:31], v[52:53]
	v_cvt_pk_bf16_f32 v0, v0, v1
	v_cvt_pk_bf16_f32 v1, v2, v3
	v_cvt_pk_bf16_f32 v2, v4, v5
	v_cvt_pk_bf16_f32 v3, v6, v7
	v_cvt_pk_bf16_f32 v4, v8, v9
	v_cvt_pk_bf16_f32 v5, v10, v11
	v_cvt_pk_bf16_f32 v6, v12, v13
	v_cvt_pk_bf16_f32 v7, v14, v15
	global_store_dwordx4 v83, v[0:3], s[24:25]
	global_store_dwordx4 v83, v[4:7], s[24:25] offset:1024
